# wa/wb/wo of layer 1 converted in the in-proj L1 idle slot instead of the gate/up L0 slot
# baseline (speedup 1.0000x reference)
;     ...
;     for (int mi = 0; mi < 7 * DEPTH; ++mi) {
;         if (!((mask >> mi) & 1u)) continue;
;         const int l = mi / 7, kind = mi - 7 * l;
;         const float* W; const float* ks = nullptr; bf16_t* WT; int K, N, rm = 0;
;         if (kind == 0)      { W = a.in[2] + (size_t)l * 2048 * 7680;  K = 2048; N = 7680; WT = (bf16_t*)(ws + WS_WIN + l * SZ_WIN); ks = a.in[1] + l * 2048; rm = 3; }
;         else if (kind == 1) { W = a.in[10] + (size_t)l * 1024 * 2048; K = 1024; N = 2048; WT = (bf16_t*)(ws + WS_WA + l * SZ_WA); }
;         else if (kind == 2) { W = a.in[11] + (size_t)l * 1024 * 2048; K = 1024; N = 2048; WT = (bf16_t*)(ws + WS_WB + l * SZ_WB); }
;         else if (kind == 3) { W = a.in[12] + (size_t)l * 2048 * 2048; K = 2048; N = 2048; WT = (bf16_t*)(ws + WS_WO + l * SZ_WO); }
;         else if (kind == 4) { W = a.in[14] + (size_t)l * 2048 * 5632; K = 2048; N = 5632; WT = (bf16_t*)(ws + WS_WGU + l * SZ_WGU); ks = a.in[13] + l * 2048; rm = 1; }
;         else if (kind == 5) { W = a.in[15] + (size_t)l * 2048 * 5632; K = 2048; N = 5632; WT = (bf16_t*)(ws + WS_WGU + l * SZ_WGU); ks = a.in[13] + l * 2048; rm = 2; }
;         else                { W = a.in[16] + (size_t)l * 5632 * 2048; K = 5632; N = 2048; WT = (bf16_t*)(ws + WS_WD + l * SZ_WD); }
.Lsl_in_dispatch:
	s_cmp_eq_u32 s28, 0
	s_cbranch_scc1 .Lsl_in_set0
	s_cmp_eq_u32 s28, 1
	s_cbranch_scc1 .Lsl_in_set1
	s_cmp_eq_u32 s28, 16
	s_cbranch_scc1 .Lsl_in_set16
	s_cmp_eq_u32 s28, 17
	s_cbranch_scc1 .Lsl_in_set17
	s_cmp_eq_u32 s28, 18
	s_cbranch_scc1 .Lsl_in_set18
	s_cmp_eq_u32 s28, 19
	s_cbranch_scc1 .Lsl_in_set19
	s_cmp_eq_u32 s28, 20
	s_cbranch_scc1 .Lsl_in_set20
	s_branch .LBB0_256
